# code placement: one 4-byte pad after the grid barrier before the down-projection GEMM phase (P12 K-loop head moves from 4 to 0 mod 8)
# speedup vs baseline: 1.0017x; 1.0017x over previous
;     __device__ bool next(int i, Unit& u) const { if (i >= n) return false; const int q = first + i; u.pm = rowbase + q % rows; u.pn = q / rows; return true; }
;     __host__ __device__ bool next(int i, Unit& u) const {
;         const long L = (long)i * G + c; if (L >= nwg) return false;
;         int wgid = (int)L; { const int q = nwg / NXCD, r = nwg % NXCD, xcd = wgid % NXCD, off = wgid / NXCD; wgid = (xcd < r ? xcd * (q + 1) : r * (q + 1) + (xcd - r) * q) + off; }
;         const int nig = WGM * nN, gid = wgid / nig, fm = gid * WGM, gsz = (nM - fm) < WGM ? (nM - fm) : WGM;
;         u.pm = fm + ((wgid % nig) % gsz); u.pn = (wgid % nig) / gsz; return true;
; __device__ __forceinline__ void xcd_barrier(const XcdBarrier& b) {
;     ...
;         }
;     }
;     __syncthreads();
; }
.LBB0_1080:
	s_or_b64 exec, exec, s[4:5]
	v_mov_b32_e32 v8, v189
	s_waitcnt lgkmcnt(0)
	s_barrier
	s_nop 0
	s_and_b64 vcc, exec, s[86:87]
	v_readfirstlane_b32 s2, v8
	s_cbranch_vccnz .LBB0_1108
	s_lshr_b32 s0, s49, 29
	s_add_i32 s5, s22, s0
	s_and_b32 s0, s5, -8
	s_sub_i32 s4, s22, s0
	s_cmp_gt_i32 s4, -1
	s_cbranch_scc0 .LBB0_1083
	s_lshl_b32 s3, s4, 6
	s_ashr_i32 s5, s5, 3
	s_cbranch_execz .LBB0_1084
	s_branch .LBB0_1085
